# hoist LayerNorm gamma/beta loads out of the row loops; drop vmcnt(0) fences in LN1/LN2
# speedup vs baseline: 1.0161x; 1.0161x over previous
.LBB0_926:
	s_andn2_b64 vcc, exec, s[4:5]
	s_cbranch_vccnz .LBB0_972
	v_readlane_b32 s10, v254, 0
	v_readlane_b32 s11, v254, 1
	s_load_dwordx4 s[4:7], s[10:11], 0xb8
	s_waitcnt vmcnt(0)
	v_mov_b32_e32 v24, v192
	s_nop 0
	v_ashrrev_i32_e32 v34, 6, v24
	v_mul_lo_u32 v72, v34, s42
	v_add_u32_e32 v0, s2, v72
	v_cmp_gt_i32_e32 vcc, s58, v0
	s_and_saveexec_b64 s[8:9], vcc
	s_cbranch_execz .LBB0_947
	s_waitcnt lgkmcnt(0)
	s_add_u32 s12, s4, 0x8000
	s_addc_u32 s13, s5, 0
	s_add_u32 s16, s6, 0x4e09000
	s_addc_u32 s17, s7, 0
	s_add_u32 s0, s6, 0x11139000
	s_addc_u32 s20, s7, 0
	v_lshlrev_b32_e32 v25, 2, v24
	s_add_u32 s14, s6, 0x151f9000
	v_readlane_b32 s22, v254, 32
	v_ashrrev_i32_e32 v1, 31, v0
	v_and_b32_e32 v26, 0xfc, v25
	s_addc_u32 s15, s7, 0
	v_readlane_b32 s23, v254, 33
	v_lshlrev_b32_e32 v22, 1, v26
	s_waitcnt vmcnt(0)
	v_lshlrev_b64 v[36:37], 11, v[0:1]
	s_add_u32 s18, s6, 0x8f19000
	v_or_b32_e32 v14, v36, v22
	v_mov_b32_e32 v15, v37
	global_load_ushort v23, v173, s[22:23]
	s_mov_b32 s22, 0xfe000000
	s_addc_u32 s19, s7, 0
	v_lshl_add_u64 v[8:9], s[14:15], 0, v[14:15]
	s_mov_b32 s23, -1
	v_lshl_add_u64 v[6:7], s[18:19], 0, v[14:15]
	v_lshl_add_u64 v[8:9], v[8:9], 0, s[22:23]
	v_cmp_gt_i32_e32 vcc, s73, v0
	v_or_b32_e32 v18, 0x400, v14
	v_mov_b32_e32 v19, v37
	v_cndmask_b32_e32 v1, v9, v7, vcc
	v_cndmask_b32_e32 v0, v8, v6, vcc
	v_or_b32_e32 v6, 0x200, v14
	v_mov_b32_e32 v7, v37
	v_lshl_add_u64 v[8:9], s[12:13], 0, v[6:7]
	v_lshl_add_u64 v[10:11], s[16:17], 0, v[6:7]
	v_lshl_add_u64 v[12:13], s[18:19], 0, v[6:7]
	v_lshl_add_u64 v[6:7], s[14:15], 0, v[6:7]
	v_lshl_add_u64 v[6:7], v[6:7], 0, s[22:23]
	v_cndmask_b32_e32 v7, v7, v13, vcc
	v_cndmask_b32_e32 v6, v6, v12, vcc
	v_lshl_add_u64 v[12:13], s[12:13], 0, v[18:19]
	v_lshl_add_u64 v[16:17], s[16:17], 0, v[18:19]
	v_lshl_add_u64 v[20:21], s[18:19], 0, v[18:19]
	v_lshl_add_u64 v[18:19], s[14:15], 0, v[18:19]
	v_lshl_add_u64 v[18:19], v[18:19], 0, s[22:23]
	v_lshl_add_u64 v[2:3], s[12:13], 0, v[14:15]
	v_lshl_add_u64 v[4:5], s[16:17], 0, v[14:15]
	v_cndmask_b32_e32 v19, v19, v21, vcc
	v_cndmask_b32_e32 v18, v18, v20, vcc
	v_or_b32_e32 v14, 0x600, v14
	global_load_dwordx2 v[20:21], v[18:19], off
	v_lshl_add_u64 v[18:19], s[12:13], 0, v[14:15]
	global_load_dwordx2 v[28:29], v[18:19], off
	v_lshl_add_u64 v[18:19], s[16:17], 0, v[14:15]
	global_load_dwordx2 v[32:33], v[18:19], off
	v_lshl_add_u64 v[18:19], s[18:19], 0, v[14:15]
	v_lshl_add_u64 v[14:15], s[14:15], 0, v[14:15]
	v_lshl_add_u64 v[14:15], v[14:15], 0, s[22:23]
	v_cndmask_b32_e32 v15, v15, v19, vcc
	v_cndmask_b32_e32 v14, v14, v18, vcc
	global_load_dwordx2 v[2:3], v[2:3], off
	s_load_dwordx4 s[16:19], s[10:11], 0x98
	global_load_dwordx2 v[4:5], v[4:5], off
	s_movk_i32 s10, 0x80
	global_load_dwordx2 v[0:1], v[0:1], off
	s_cmp_eq_u32 s78, 3
	global_load_dwordx2 v[8:9], v[8:9], off
	v_bitop3_b32 v73, v25, s10, v200 bitop3:0x6c
	global_load_dwordx2 v[10:11], v[10:11], off
	s_cselect_b64 s[10:11], -1, 0
	global_load_dwordx2 v[6:7], v[6:7], off
	s_and_b64 s[12:13], s[10:11], exec
	global_load_dwordx2 v[12:13], v[12:13], off
	v_readlane_b32 s12, v253, 32
	global_load_dwordx2 v[16:17], v[16:17], off
	s_cselect_b32 s21, s20, 0
	global_load_dwordx2 v[40:41], v[14:15], off
	s_cselect_b32 s20, s0, 0
	v_readlane_b32 s13, v253, 33
	s_mov_b32 s23, s13
	s_lshl_b32 s22, s78, 10
	s_lshl_b64 s[22:23], s[22:23], 2
	v_writelane_b32 v253, s12, 32
	v_lshlrev_b32_e32 v172, 2, v26
	v_and_b32_e32 v24, 63, v24
	v_writelane_b32 v253, s13, 33
	v_bitop3_b32 v74, v25, 64, v200 bitop3:0x6c
	v_bitop3_b32 v75, v25, 32, v200 bitop3:0x6c
	v_bitop3_b32 v76, v25, 16, v200 bitop3:0x6c
	v_bitop3_b32 v77, v25, 8, v200 bitop3:0x6c
	v_bitop3_b32 v78, v25, 4, v200 bitop3:0x6c
	v_lshlrev_b32_e32 v24, 3, v24
	v_mov_b32_e32 v25, v173
	v_lshl_add_u64 v[26:27], s[6:7], 0, v[36:37]
	v_lshl_add_u64 v[30:31], s[4:5], 0, v[36:37]
	v_lshl_add_u64 v[36:37], s[20:21], 0, v[36:37]
	s_mov_b32 s20, s78
	s_waitcnt vmcnt(12)
	v_readfirstlane_b32 s0, v23
	s_lshr_b32 s0, s0, 6
	s_nop 0
	v_add_u32_e32 v34, s0, v34
	s_waitcnt lgkmcnt(0)
	s_add_u32 s18, s18, s22
	v_mul_lo_u32 v79, s42, v34
	s_addc_u32 s19, s19, s23
	v_add_u32_e32 v34, s2, v79
	s_mul_i32 s12, s42, s0
	s_add_u32 s16, s16, s22
	v_ashrrev_i32_e32 v35, 31, v34
	s_addc_u32 s17, s17, s23
	v_mov_b32_e32 v23, v173
	s_ashr_i32 s13, s12, 31
	v_lshlrev_b64 v[38:39], 11, v[34:35]
	v_lshl_add_u64 v[14:15], s[16:17], 0, v[172:173]
	v_lshl_add_u64 v[18:19], s[18:19], 0, v[172:173]
	v_lshl_add_u64 v[22:23], s[14:15], 0, v[22:23]
	s_lshl_b64 s[14:15], s[12:13], 11
	v_lshl_add_u64 v[34:35], s[6:7], 0, v[38:39]
	v_lshl_add_u64 v[38:39], s[4:5], 0, v[38:39]
	s_mov_b64 s[16:17], 0
	s_mov_b32 s0, s2
	global_load_dwordx4 v[84:87], v[14:15], off
	global_load_dwordx4 v[88:91], v[18:19], off
	global_load_dwordx4 v[92:95], v[14:15], off offset:1024
	global_load_dwordx4 v[96:99], v[18:19], off offset:1024
	global_load_dwordx4 v[100:103], v[14:15], off offset:2048
	global_load_dwordx4 v[104:107], v[18:19], off offset:2048
	global_load_dwordx4 v[108:111], v[14:15], off offset:3072
	global_load_dwordx4 v[112:115], v[18:19], off offset:3072
	s_waitcnt vmcnt(0)
	s_branch .LBB0_930

.LBB0_939:
	s_or_b64 exec, exec, s[4:5]
	ds_bpermute_b32 v61, v73, v57
	ds_bpermute_b32 v60, v73, v56
	s_mov_b32 s4, 0x3a800000
	s_waitcnt lgkmcnt(0)
	v_pk_add_f32 v[56:57], v[56:57], v[60:61]
	ds_bpermute_b32 v61, v74, v57
	ds_bpermute_b32 v60, v74, v56
	s_waitcnt lgkmcnt(0)
	v_pk_add_f32 v[56:57], v[56:57], v[60:61]
	ds_bpermute_b32 v61, v75, v57
	ds_bpermute_b32 v60, v75, v56
	s_waitcnt lgkmcnt(0)
	v_pk_add_f32 v[56:57], v[56:57], v[60:61]
	ds_bpermute_b32 v61, v76, v57
	ds_bpermute_b32 v60, v76, v56
	s_waitcnt lgkmcnt(0)
	v_pk_add_f32 v[56:57], v[56:57], v[60:61]
	ds_bpermute_b32 v61, v77, v57
	ds_bpermute_b32 v60, v77, v56
	s_waitcnt lgkmcnt(0)
	v_pk_add_f32 v[56:57], v[56:57], v[60:61]
	ds_bpermute_b32 v61, v78, v57
	ds_bpermute_b32 v60, v78, v56
	s_waitcnt lgkmcnt(0)
	v_pk_add_f32 v[56:57], v[56:57], v[60:61]
	s_nop 0
	v_pk_mul_f32 v[60:61], v[56:57], s[4:5] op_sel_hi:[1,0]
	s_nop 0
	v_fma_f32 v56, -v61, v61, v60
	v_max_f32_e32 v56, 0, v56
	v_add_f32_e32 v56, 0x3727c5ac, v56
	v_cmp_gt_f32_e32 vcc, s86, v56
	v_mul_f32_e32 v57, 0x4b800000, v56
	v_sub_f32_e32 v49, v49, v61
	v_cndmask_b32_e32 v56, v56, v57, vcc
	v_rsq_f32_e32 v56, v56
	v_sub_f32_e32 v48, v48, v61
	v_sub_f32_e32 v47, v47, v61
	v_sub_f32_e32 v46, v46, v61
	v_mul_f32_e32 v57, 0x45800000, v56
	v_cndmask_b32_e32 v56, v56, v57, vcc
	v_pk_mul_f32 v[48:49], v[48:49], v[56:57] op_sel_hi:[1,0]
	v_pk_mul_f32 v[46:47], v[46:47], v[56:57] op_sel_hi:[1,0]
	v_pk_fma_f32 v[64:65], v[84:85], v[48:49], v[88:89]
	v_pk_fma_f32 v[62:63], v[86:87], v[46:47], v[90:91]
	v_bfe_u32 v46, v64, 16, 1
	v_add3_u32 v60, v64, v46, s96
	v_bfe_u32 v46, v65, 16, 1
	v_add3_u32 v46, v65, v46, s96
	v_and_b32_e32 v66, 0xffff0000, v46
	v_bfe_u32 v46, v62, 16, 1
	v_add3_u32 v67, v62, v46, s96
	v_bfe_u32 v46, v63, 16, 1
	v_add3_u32 v46, v63, v46, s96
	v_and_b32_e32 v69, 0xffff0000, v46
	v_lshl_add_u64 v[46:47], v[30:31], 0, v[24:25]
	v_add_co_u32_e32 v48, vcc, 0x8000, v46
	v_or_b32_sdwa v70, v66, v60 dst_sel:DWORD dst_unused:UNUSED_PAD src0_sel:DWORD src1_sel:WORD_1
	v_or_b32_sdwa v71, v67, v69 dst_sel:DWORD dst_unused:UNUSED_PAD src0_sel:WORD_1 src1_sel:DWORD
	v_addc_co_u32_e32 v49, vcc, 0, v47, vcc
	global_store_dwordx2 v[48:49], v[70:71], off
	v_cndmask_b32_e64 v48, 0, 1, s[10:11]
	v_cmp_ne_u32_e64 s[4:5], 1, v48
	s_andn2_b64 vcc, exec, s[10:11]
	v_lshl_add_u64 v[48:49], v[36:37], 0, v[24:25]
	s_cbranch_vccnz .LBB0_941
	global_store_dwordx2 v[48:49], v[70:71], off
.LBB0_941:
	v_and_b32_e32 v68, 0xffff0000, v60
	v_and_b32_e32 v67, 0xffff0000, v67
	v_mov_b32_e32 v70, v65
	v_mov_b32_e32 v71, v62
	v_mov_b32_e32 v65, v63
	v_pk_add_f32 v[66:67], v[70:71], v[66:67] neg_lo:[0,1] neg_hi:[0,1]
	v_pk_add_f32 v[62:63], v[64:65], v[68:69] neg_lo:[0,1] neg_hi:[0,1]
	v_and_b32_sdwa v64, v66, v196 dst_sel:DWORD dst_unused:UNUSED_PAD src0_sel:WORD_1 src1_sel:DWORD
	v_and_b32_sdwa v65, v63, v196 dst_sel:DWORD dst_unused:UNUSED_PAD src0_sel:WORD_1 src1_sel:DWORD
	v_and_b32_sdwa v60, v67, v196 dst_sel:DWORD dst_unused:UNUSED_PAD src0_sel:WORD_1 src1_sel:DWORD
	v_add3_u32 v64, v66, v64, s96
	v_and_b32_sdwa v66, v62, v196 dst_sel:DWORD dst_unused:UNUSED_PAD src0_sel:WORD_1 src1_sel:DWORD
	v_add3_u32 v63, v63, v65, s96
	v_add3_u32 v60, v67, v60, s96
	v_and_b32_e32 v64, 0xffff0000, v64
	v_add3_u32 v62, v62, v66, s96
	v_and_b32_e32 v63, 0xffff0000, v63
	v_or_b32_sdwa v65, v60, v63 dst_sel:DWORD dst_unused:UNUSED_PAD src0_sel:WORD_1 src1_sel:DWORD
	v_or_b32_sdwa v64, v64, v62 dst_sel:DWORD dst_unused:UNUSED_PAD src0_sel:DWORD src1_sel:WORD_1
	v_lshl_add_u64 v[62:63], v[26:27], 0, v[24:25]
	s_mov_b32 s13, 0x4e09000
	v_add_co_u32_e32 v62, vcc, s13, v62
	v_mov_b32_e32 v57, v56
	s_nop 0
	v_addc_co_u32_e32 v63, vcc, 0, v63, vcc
	global_store_dwordx2 v[62:63], v[64:65], off
	v_sub_f32_e32 v81, v53, v61
	v_sub_f32_e32 v80, v52, v61
	v_sub_f32_e32 v59, v59, v61
	v_sub_f32_e32 v58, v58, v61
	v_mov_b32_e32 v52, v56
	v_mov_b32_e32 v53, v56
	v_pk_mul_f32 v[82:83], v[58:59], v[52:53]
	v_pk_mul_f32 v[58:59], v[80:81], v[56:57]
	v_add_co_u32_e32 v80, vcc, 0x8000, v46
	v_pk_fma_f32 v[58:59], v[58:59], v[92:93], v[96:97]
	v_pk_fma_f32 v[64:65], v[82:83], v[94:95], v[98:99]
	v_bfe_u32 v66, v59, 16, 1
	v_bfe_u32 v68, v65, 16, 1
	v_bfe_u32 v60, v58, 16, 1
	v_add3_u32 v66, v59, v66, s96
	v_bfe_u32 v67, v64, 16, 1
	v_add3_u32 v68, v65, v68, s96
	v_add3_u32 v60, v58, v60, s96
	v_and_b32_e32 v66, 0xffff0000, v66
	v_add3_u32 v67, v64, v67, s96
	v_and_b32_e32 v69, 0xffff0000, v68
	v_addc_co_u32_e32 v81, vcc, 0, v47, vcc
	v_or_b32_sdwa v70, v66, v60 dst_sel:DWORD dst_unused:UNUSED_PAD src0_sel:DWORD src1_sel:WORD_1
	v_or_b32_sdwa v71, v67, v69 dst_sel:DWORD dst_unused:UNUSED_PAD src0_sel:WORD_1 src1_sel:DWORD
	s_and_b64 vcc, exec, s[4:5]
	global_store_dwordx2 v[80:81], v[70:71], off offset:512
	s_cbranch_vccnz .LBB0_943
	global_store_dwordx2 v[48:49], v[70:71], off offset:512
.LBB0_943:
	v_and_b32_e32 v68, 0xffff0000, v60
	v_and_b32_e32 v67, 0xffff0000, v67
	v_mov_b32_e32 v70, v59
	v_mov_b32_e32 v71, v64
	v_mov_b32_e32 v59, v65
	v_pk_add_f32 v[66:67], v[70:71], v[66:67] neg_lo:[0,1] neg_hi:[0,1]
	v_pk_add_f32 v[58:59], v[58:59], v[68:69] neg_lo:[0,1] neg_hi:[0,1]
	v_and_b32_sdwa v64, v66, v196 dst_sel:DWORD dst_unused:UNUSED_PAD src0_sel:WORD_1 src1_sel:DWORD
	v_and_b32_sdwa v65, v59, v196 dst_sel:DWORD dst_unused:UNUSED_PAD src0_sel:WORD_1 src1_sel:DWORD
	v_and_b32_sdwa v60, v67, v196 dst_sel:DWORD dst_unused:UNUSED_PAD src0_sel:WORD_1 src1_sel:DWORD
	v_add3_u32 v64, v66, v64, s96
	v_and_b32_sdwa v66, v58, v196 dst_sel:DWORD dst_unused:UNUSED_PAD src0_sel:WORD_1 src1_sel:DWORD
	v_add3_u32 v59, v59, v65, s96
	v_add3_u32 v60, v67, v60, s96
	v_and_b32_e32 v64, 0xffff0000, v64
	v_add3_u32 v58, v58, v66, s96
	v_and_b32_e32 v59, 0xffff0000, v59
	v_or_b32_sdwa v59, v60, v59 dst_sel:DWORD dst_unused:UNUSED_PAD src0_sel:WORD_1 src1_sel:DWORD
	v_or_b32_sdwa v58, v64, v58 dst_sel:DWORD dst_unused:UNUSED_PAD src0_sel:DWORD src1_sel:WORD_1
	global_store_dwordx2 v[62:63], v[58:59], off offset:512
	v_sub_f32_e32 v43, v43, v61
	v_sub_f32_e32 v42, v42, v61
	v_sub_f32_e32 v55, v55, v61
	v_sub_f32_e32 v54, v54, v61
	v_pk_mul_f32 v[52:53], v[54:55], v[52:53]
	v_pk_mul_f32 v[42:43], v[42:43], v[56:57]
	v_pk_fma_f32 v[52:53], v[52:53], v[102:103], v[106:107]
	v_pk_fma_f32 v[42:43], v[42:43], v[100:101], v[104:105]
	v_bfe_u32 v58, v52, 16, 1
	v_bfe_u32 v54, v42, 16, 1
	v_add3_u32 v55, v42, v54, s96
	v_bfe_u32 v54, v43, 16, 1
	v_add3_u32 v60, v52, v58, s96
	v_bfe_u32 v58, v53, 16, 1
	v_add3_u32 v54, v43, v54, s96
	v_add3_u32 v58, v53, v58, s96
	v_add_co_u32_e32 v66, vcc, 0x8000, v46
	v_and_b32_e32 v54, 0xffff0000, v54
	v_and_b32_e32 v59, 0xffff0000, v58
	v_addc_co_u32_e32 v67, vcc, 0, v47, vcc
	v_or_b32_sdwa v64, v54, v55 dst_sel:DWORD dst_unused:UNUSED_PAD src0_sel:DWORD src1_sel:WORD_1
	v_or_b32_sdwa v65, v60, v59 dst_sel:DWORD dst_unused:UNUSED_PAD src0_sel:WORD_1 src1_sel:DWORD
	s_and_b64 vcc, exec, s[4:5]
	global_store_dwordx2 v[66:67], v[64:65], off offset:1024
	s_cbranch_vccnz .LBB0_945
	global_store_dwordx2 v[48:49], v[64:65], off offset:1024
.LBB0_945:
	v_and_b32_e32 v58, 0xffff0000, v55
	v_and_b32_e32 v55, 0xffff0000, v60
	v_mov_b32_e32 v64, v43
	v_mov_b32_e32 v65, v52
	v_pk_add_f32 v[54:55], v[64:65], v[54:55] neg_lo:[0,1] neg_hi:[0,1]
	v_mov_b32_e32 v43, v53
	v_pk_add_f32 v[42:43], v[42:43], v[58:59] neg_lo:[0,1] neg_hi:[0,1]
	v_and_b32_sdwa v53, v54, v196 dst_sel:DWORD dst_unused:UNUSED_PAD src0_sel:WORD_1 src1_sel:DWORD
	v_and_b32_sdwa v52, v55, v196 dst_sel:DWORD dst_unused:UNUSED_PAD src0_sel:WORD_1 src1_sel:DWORD
	v_add3_u32 v53, v54, v53, s96
	v_and_b32_sdwa v54, v43, v196 dst_sel:DWORD dst_unused:UNUSED_PAD src0_sel:WORD_1 src1_sel:DWORD
	v_add3_u32 v52, v55, v52, s96
	v_and_b32_sdwa v55, v42, v196 dst_sel:DWORD dst_unused:UNUSED_PAD src0_sel:WORD_1 src1_sel:DWORD
	v_add3_u32 v43, v43, v54, s96
	v_and_b32_e32 v53, 0xffff0000, v53
	v_add3_u32 v42, v42, v55, s96
	v_and_b32_e32 v43, 0xffff0000, v43
	v_or_b32_sdwa v43, v52, v43 dst_sel:DWORD dst_unused:UNUSED_PAD src0_sel:WORD_1 src1_sel:DWORD
	v_or_b32_sdwa v42, v53, v42 dst_sel:DWORD dst_unused:UNUSED_PAD src0_sel:DWORD src1_sel:WORD_1
	global_store_dwordx2 v[62:63], v[42:43], off offset:1024
	v_sub_f32_e32 v43, v51, v61
	v_sub_f32_e32 v42, v50, v61
	v_sub_f32_e32 v45, v45, v61
	v_sub_f32_e32 v44, v44, v61
	v_mov_b32_e32 v50, v56
	v_mov_b32_e32 v51, v56
	v_pk_mul_f32 v[44:45], v[44:45], v[50:51]
	v_pk_mul_f32 v[42:43], v[42:43], v[56:57]
	v_add_co_u32_e32 v58, vcc, 0x8000, v46
	v_pk_fma_f32 v[42:43], v[42:43], v[108:109], v[112:113]
	v_pk_fma_f32 v[44:45], v[44:45], v[110:111], v[114:115]
	v_addc_co_u32_e32 v59, vcc, 0, v47, vcc
	v_bfe_u32 v47, v43, 16, 1
	v_bfe_u32 v52, v45, 16, 1
	v_bfe_u32 v46, v42, 16, 1
	v_bfe_u32 v50, v44, 16, 1
	v_add3_u32 v47, v43, v47, s96
	v_add3_u32 v52, v45, v52, s96
	v_add3_u32 v46, v42, v46, s96
	v_add3_u32 v51, v44, v50, s96
	v_and_b32_e32 v50, 0xffff0000, v47
	v_and_b32_e32 v47, 0xffff0000, v52
	v_or_b32_sdwa v52, v50, v46 dst_sel:DWORD dst_unused:UNUSED_PAD src0_sel:DWORD src1_sel:WORD_1
	v_or_b32_sdwa v53, v51, v47 dst_sel:DWORD dst_unused:UNUSED_PAD src0_sel:WORD_1 src1_sel:DWORD
	s_and_b64 vcc, exec, s[4:5]
	global_store_dwordx2 v[58:59], v[52:53], off offset:1536
	s_cbranch_vccnz .LBB0_929
	global_store_dwordx2 v[48:49], v[52:53], off offset:1536
	s_branch .LBB0_929

.LBB0_1108:
	s_or_b64 exec, exec, s[16:17]
	s_and_saveexec_b64 s[30:31], vcc
	s_cbranch_execz .LBB0_1241
	v_readlane_b32 s4, v253, 32
	s_load_dwordx4 s[16:19], s[34:35], 0x58
	s_add_u32 s34, s12, 0x3bb0000
	v_readlane_b32 s5, v253, 33
	s_addc_u32 s35, s13, 0
	s_mov_b32 s37, s5
	s_lshl_b32 s36, s78, 10
	v_writelane_b32 v253, s4, 32
	v_lshlrev_b32_e32 v172, 4, v2
	v_mov_b32_e32 v41, v173
	v_writelane_b32 v253, s5, 33
	s_lshl_b64 s[4:5], s[36:37], 2
	s_add_u32 s8, s8, s4
	s_addc_u32 s9, s9, s5
	s_add_u32 s10, s10, s4
	s_addc_u32 s11, s11, s5
	s_cmp_eq_u32 s78, 1
	s_cselect_b64 s[36:37], -1, 0
	s_and_b32 s0, 0xffff, s0
	s_lshr_b32 s0, s0, 6
	s_mul_i32 s38, s42, s0
	v_lshl_add_u64 v[30:31], s[8:9], 0, v[172:173]
	v_lshl_add_u64 v[32:33], s[10:11], 0, v[172:173]
	v_lshlrev_b32_e32 v172, 3, v2
	v_readlane_b32 s0, v253, 28
	v_or_b32_e32 v40, 0x200, v172
	v_or_b32_e32 v44, 0x400, v172
	v_mov_b32_e32 v45, v173
	v_or_b32_e32 v48, 0x600, v172
	v_mov_b32_e32 v49, v173
	v_add_u32_e32 v52, s0, v3
	s_waitcnt lgkmcnt(0)
	v_mov_b64_e32 v[54:55], s[16:17]
	s_mov_b32 s0, 0x8100
	v_lshlrev_b32_e32 v28, 2, v2
	v_cmp_eq_u32_e64 s[4:5], 0, v2
	v_lshl_add_u64 v[34:35], s[6:7], 0, v[172:173]
	v_lshl_add_u64 v[38:39], s[6:7], 0, v[40:41]
	v_lshl_add_u64 v[42:43], s[6:7], 0, v[44:45]
	v_lshl_add_u64 v[46:47], s[6:7], 0, v[48:49]
	v_mad_u64_u32 v[54:55], s[6:7], v2, s0, v[54:55]
	v_lshlrev_b64 v[2:3], 11, v[0:1]
	v_or_b32_e32 v2, v2, v172
	v_lshl_add_u64 v[56:57], s[14:15], 0, v[2:3]
	s_mov_b64 s[6:7], 0x4e09004
	v_lshl_add_u64 v[56:57], v[56:57], 0, s[6:7]
	s_ashr_i32 s39, s38, 31
	v_lshl_add_u64 v[2:3], s[12:13], 0, v[2:3]
	s_mov_b64 s[6:7], 0x8004
	v_xor_b32_e32 v29, 0x80, v28
	v_xor_b32_e32 v86, 64, v28
	v_xor_b32_e32 v87, 32, v28
	v_xor_b32_e32 v88, 16, v28
	v_xor_b32_e32 v89, 8, v28
	v_xor_b32_e32 v90, 4, v28
	v_lshl_add_u64 v[36:37], s[20:21], 0, v[172:173]
	v_lshl_add_u64 v[40:41], s[20:21], 0, v[40:41]
	v_lshl_add_u64 v[44:45], s[20:21], 0, v[44:45]
	v_lshl_add_u64 v[48:49], s[20:21], 0, v[48:49]
	v_lshl_add_u64 v[50:51], s[14:15], 0, v[172:173]
	v_or_b32_e32 v91, 3, v28
	s_lshl_b64 s[44:45], s[38:39], 11
	v_lshl_add_u64 v[58:59], v[2:3], 0, s[6:7]
	s_mov_b64 s[54:55], 0
	global_load_dwordx4 v[140:143], v[30:31], off
	global_load_dwordx4 v[144:147], v[32:33], off
	global_load_dwordx4 v[148:151], v[30:31], off offset:1024
	global_load_dwordx4 v[152:155], v[32:33], off offset:1024
	global_load_dwordx4 v[156:159], v[30:31], off offset:2048
	global_load_dwordx4 v[160:163], v[32:33], off offset:2048
	global_load_dwordx4 v[164:167], v[30:31], off offset:3072
	global_load_dwordx4 v[168:171], v[32:33], off offset:3072
	s_waitcnt vmcnt(0)
	s_branch .LBB0_1112

.LBB0_1118:
	s_or_b64 exec, exec, s[8:9]
	ds_bpermute_b32 v79, v29, v77
	ds_bpermute_b32 v78, v29, v76
	s_mov_b32 s0, 0x3a800000
	s_mov_b64 s[10:11], -1
	s_waitcnt lgkmcnt(0)
	v_pk_add_f32 v[76:77], v[76:77], v[78:79]
	ds_bpermute_b32 v79, v86, v77
	ds_bpermute_b32 v78, v86, v76
	s_waitcnt lgkmcnt(0)
	v_pk_add_f32 v[76:77], v[76:77], v[78:79]
	ds_bpermute_b32 v79, v87, v77
	ds_bpermute_b32 v78, v87, v76
	s_waitcnt lgkmcnt(0)
	v_pk_add_f32 v[76:77], v[76:77], v[78:79]
	ds_bpermute_b32 v79, v88, v77
	ds_bpermute_b32 v78, v88, v76
	s_waitcnt lgkmcnt(0)
	v_pk_add_f32 v[76:77], v[76:77], v[78:79]
	ds_bpermute_b32 v79, v89, v77
	ds_bpermute_b32 v78, v89, v76
	s_waitcnt lgkmcnt(0)
	v_pk_add_f32 v[76:77], v[76:77], v[78:79]
	ds_bpermute_b32 v79, v90, v77
	ds_bpermute_b32 v78, v90, v76
	s_waitcnt lgkmcnt(0)
	v_pk_add_f32 v[76:77], v[76:77], v[78:79]
	s_nop 0
	v_pk_mul_f32 v[78:79], v[76:77], s[0:1] op_sel_hi:[1,0]
	s_nop 0
	v_fma_f32 v1, -v79, v79, v78
	v_max_f32_e32 v1, 0, v1
	v_add_f32_e32 v1, 0x3727c5ac, v1
	v_cmp_gt_f32_e32 vcc, s86, v1
	v_mul_f32_e32 v53, 0x4b800000, v1
	v_sub_f32_e32 v3, v3, v79
	v_cndmask_b32_e32 v1, v1, v53, vcc
	v_rsq_f32_e32 v1, v1
	v_sub_f32_e32 v2, v2, v79
	v_mul_f32_e32 v53, 0x45800000, v1
	v_cndmask_b32_e32 v80, v1, v53, vcc
	v_mul_hi_i32 v1, v0, s59
	v_lshrrev_b32_e32 v53, 31, v1
	v_ashrrev_i32_e32 v1, 7, v1
	v_add_u32_e32 v76, v1, v53
	v_mul_i32_i24_e32 v1, 0x810, v76
	v_sub_u32_e32 v78, v0, v1
	v_ashrrev_i32_e32 v1, 31, v0
	v_lshlrev_b64 v[82:83], 10, v[0:1]
	v_sub_f32_e32 v1, v75, v79
	v_sub_f32_e32 v0, v74, v79
	v_pk_mul_f32 v[74:75], v[2:3], v[80:81] op_sel_hi:[1,0]
	v_pk_mul_f32 v[0:1], v[0:1], v[80:81] op_sel_hi:[1,0]
	v_cmp_lt_i32_e64 s[8:9], 15, v78
	s_and_b64 vcc, exec, s[26:27]
	v_pk_fma_f32 v[2:3], v[142:143], v[0:1], v[146:147]
	v_pk_fma_f32 v[0:1], v[140:141], v[74:75], v[144:145]
	v_lshlrev_b64 v[74:75], 1, v[82:83]
	s_cbranch_vccz .LBB0_1120
	v_and_b32_sdwa v53, v3, v196 dst_sel:DWORD dst_unused:UNUSED_PAD src0_sel:WORD_1 src1_sel:DWORD
	v_and_b32_sdwa v81, v1, v196 dst_sel:DWORD dst_unused:UNUSED_PAD src0_sel:WORD_1 src1_sel:DWORD
	v_and_b32_sdwa v61, v0, v196 dst_sel:DWORD dst_unused:UNUSED_PAD src0_sel:WORD_1 src1_sel:DWORD
	v_add3_u32 v53, v3, v53, s96
	v_and_b32_sdwa v77, v2, v196 dst_sel:DWORD dst_unused:UNUSED_PAD src0_sel:WORD_1 src1_sel:DWORD
	v_add3_u32 v81, v1, v81, s96
	v_add3_u32 v61, v0, v61, s96
	v_add3_u32 v77, v2, v77, s96
	v_and_b32_e32 v94, 0xffff0000, v81
	v_and_b32_e32 v99, 0xffff0000, v53
	v_lshl_add_u64 v[82:83], v[34:35], 0, v[74:75]
	v_mov_b32_e32 v84, v0
	v_mov_b32_e32 v85, v3
	v_mov_b32_e32 v92, v1
	v_mov_b32_e32 v93, v2
	v_and_b32_e32 v95, 0xffff0000, v77
	v_or_b32_sdwa v96, v94, v61 dst_sel:DWORD dst_unused:UNUSED_PAD src0_sel:DWORD src1_sel:WORD_1
	v_and_b32_e32 v98, 0xffff0000, v61
	v_or_b32_sdwa v97, v77, v99 dst_sel:DWORD dst_unused:UNUSED_PAD src0_sel:WORD_1 src1_sel:DWORD
	global_store_dwordx2 v[82:83], v[96:97], off
	v_pk_add_f32 v[82:83], v[92:93], v[94:95] neg_lo:[0,1] neg_hi:[0,1]
	v_pk_add_f32 v[84:85], v[84:85], v[98:99] neg_lo:[0,1] neg_hi:[0,1]
	v_and_b32_sdwa v61, v82, v196 dst_sel:DWORD dst_unused:UNUSED_PAD src0_sel:WORD_1 src1_sel:DWORD
	v_and_b32_sdwa v77, v85, v196 dst_sel:DWORD dst_unused:UNUSED_PAD src0_sel:WORD_1 src1_sel:DWORD
	v_and_b32_sdwa v53, v83, v196 dst_sel:DWORD dst_unused:UNUSED_PAD src0_sel:WORD_1 src1_sel:DWORD
	v_add3_u32 v61, v82, v61, s96
	v_and_b32_sdwa v81, v84, v196 dst_sel:DWORD dst_unused:UNUSED_PAD src0_sel:WORD_1 src1_sel:DWORD
	v_add3_u32 v77, v85, v77, s96
	v_add3_u32 v53, v83, v53, s96
	v_and_b32_e32 v61, 0xffff0000, v61
	v_add3_u32 v81, v84, v81, s96
	v_and_b32_e32 v77, 0xffff0000, v77
	v_or_b32_sdwa v83, v53, v77 dst_sel:DWORD dst_unused:UNUSED_PAD src0_sel:WORD_1 src1_sel:DWORD
	v_or_b32_sdwa v82, v61, v81 dst_sel:DWORD dst_unused:UNUSED_PAD src0_sel:DWORD src1_sel:WORD_1
	v_lshl_add_u64 v[84:85], v[36:37], 0, v[74:75]
	global_store_dwordx2 v[84:85], v[82:83], off
	s_mov_b64 s[10:11], 0

.LBB0_1124:
	v_mov_b32_e32 v81, v80
	v_sub_f32_e32 v73, v73, v79
	v_sub_f32_e32 v72, v72, v79
	v_sub_f32_e32 v71, v71, v79
	v_sub_f32_e32 v70, v70, v79
	v_mov_b32_e32 v96, v80
	v_mov_b32_e32 v97, v80
	v_pk_mul_f32 v[70:71], v[70:71], v[80:81]
	v_pk_mul_f32 v[72:73], v[72:73], v[96:97]
	v_cndmask_b32_e64 v53, 0, 1, s[26:27]
	s_mov_b64 s[56:57], -1
	v_cmp_ne_u32_e64 s[10:11], 1, v53
	s_andn2_b64 vcc, exec, s[26:27]
	v_pk_fma_f32 v[2:3], v[72:73], v[150:151], v[154:155]
	v_pk_fma_f32 v[0:1], v[70:71], v[148:149], v[152:153]
	s_cbranch_vccnz .LBB0_1126
	v_and_b32_sdwa v53, v3, v196 dst_sel:DWORD dst_unused:UNUSED_PAD src0_sel:WORD_1 src1_sel:DWORD
	v_and_b32_sdwa v94, v1, v196 dst_sel:DWORD dst_unused:UNUSED_PAD src0_sel:WORD_1 src1_sel:DWORD
	v_and_b32_sdwa v61, v0, v196 dst_sel:DWORD dst_unused:UNUSED_PAD src0_sel:WORD_1 src1_sel:DWORD
	v_add3_u32 v53, v3, v53, s96
	v_and_b32_sdwa v77, v2, v196 dst_sel:DWORD dst_unused:UNUSED_PAD src0_sel:WORD_1 src1_sel:DWORD
	v_add3_u32 v94, v1, v94, s96
	v_add3_u32 v61, v0, v61, s96
	v_add3_u32 v77, v2, v77, s96
	v_and_b32_e32 v94, 0xffff0000, v94
	v_and_b32_e32 v99, 0xffff0000, v53
	v_lshl_add_u64 v[70:71], v[38:39], 0, v[74:75]
	v_mov_b32_e32 v92, v1
	v_mov_b32_e32 v93, v2
	v_and_b32_e32 v95, 0xffff0000, v77
	v_or_b32_sdwa v96, v94, v61 dst_sel:DWORD dst_unused:UNUSED_PAD src0_sel:DWORD src1_sel:WORD_1
	v_or_b32_sdwa v97, v77, v99 dst_sel:DWORD dst_unused:UNUSED_PAD src0_sel:WORD_1 src1_sel:DWORD
	v_mov_b32_e32 v72, v0
	v_mov_b32_e32 v73, v3
	v_and_b32_e32 v98, 0xffff0000, v61
	global_store_dwordx2 v[70:71], v[96:97], off
	v_pk_add_f32 v[70:71], v[92:93], v[94:95] neg_lo:[0,1] neg_hi:[0,1]
	v_pk_add_f32 v[72:73], v[72:73], v[98:99] neg_lo:[0,1] neg_hi:[0,1]
	v_and_b32_sdwa v61, v70, v196 dst_sel:DWORD dst_unused:UNUSED_PAD src0_sel:WORD_1 src1_sel:DWORD
	v_and_b32_sdwa v53, v71, v196 dst_sel:DWORD dst_unused:UNUSED_PAD src0_sel:WORD_1 src1_sel:DWORD
	v_add3_u32 v61, v70, v61, s96
	v_and_b32_sdwa v70, v73, v196 dst_sel:DWORD dst_unused:UNUSED_PAD src0_sel:WORD_1 src1_sel:DWORD
	v_add3_u32 v53, v71, v53, s96
	v_and_b32_sdwa v71, v72, v196 dst_sel:DWORD dst_unused:UNUSED_PAD src0_sel:WORD_1 src1_sel:DWORD
	v_add3_u32 v70, v73, v70, s96
	v_and_b32_e32 v61, 0xffff0000, v61
	v_add3_u32 v72, v72, v71, s96
	v_and_b32_e32 v70, 0xffff0000, v70
	v_or_b32_sdwa v71, v53, v70 dst_sel:DWORD dst_unused:UNUSED_PAD src0_sel:WORD_1 src1_sel:DWORD
	v_or_b32_sdwa v70, v61, v72 dst_sel:DWORD dst_unused:UNUSED_PAD src0_sel:DWORD src1_sel:WORD_1
	v_lshl_add_u64 v[72:73], v[40:41], 0, v[74:75]
	s_mov_b64 s[56:57], 0
	global_store_dwordx2 v[72:73], v[70:71], off

.LBB0_1130:
	v_sub_f32_e32 v69, v69, v79
	v_sub_f32_e32 v68, v68, v79
	v_sub_f32_e32 v67, v67, v79
	v_sub_f32_e32 v66, v66, v79
	v_mov_b32_e32 v92, v80
	v_mov_b32_e32 v93, v80
	v_pk_mul_f32 v[66:67], v[66:67], v[80:81]
	v_pk_mul_f32 v[68:69], v[68:69], v[92:93]
	s_and_b64 vcc, exec, s[10:11]
	s_mov_b64 s[56:57], -1
	v_pk_fma_f32 v[2:3], v[68:69], v[158:159], v[162:163]
	v_pk_fma_f32 v[0:1], v[66:67], v[156:157], v[160:161]
	s_cbranch_vccnz .LBB0_1132
	v_and_b32_sdwa v53, v3, v196 dst_sel:DWORD dst_unused:UNUSED_PAD src0_sel:WORD_1 src1_sel:DWORD
	v_and_b32_sdwa v72, v2, v196 dst_sel:DWORD dst_unused:UNUSED_PAD src0_sel:WORD_1 src1_sel:DWORD
	v_and_b32_sdwa v73, v1, v196 dst_sel:DWORD dst_unused:UNUSED_PAD src0_sel:WORD_1 src1_sel:DWORD
	v_and_b32_sdwa v61, v0, v196 dst_sel:DWORD dst_unused:UNUSED_PAD src0_sel:WORD_1 src1_sel:DWORD
	v_add3_u32 v53, v3, v53, s96
	v_add3_u32 v77, v2, v72, s96
	v_add3_u32 v72, v1, v73, s96
	v_add3_u32 v61, v0, v61, s96
	v_and_b32_e32 v72, 0xffff0000, v72
	v_and_b32_e32 v95, 0xffff0000, v53
	v_lshl_add_u64 v[66:67], v[42:43], 0, v[74:75]
	v_mov_b32_e32 v70, v1
	v_mov_b32_e32 v71, v2
	v_and_b32_e32 v73, 0xffff0000, v77
	v_or_b32_sdwa v92, v72, v61 dst_sel:DWORD dst_unused:UNUSED_PAD src0_sel:DWORD src1_sel:WORD_1
	v_or_b32_sdwa v93, v77, v95 dst_sel:DWORD dst_unused:UNUSED_PAD src0_sel:WORD_1 src1_sel:DWORD
	v_mov_b32_e32 v68, v0
	v_mov_b32_e32 v69, v3
	v_and_b32_e32 v94, 0xffff0000, v61
	global_store_dwordx2 v[66:67], v[92:93], off
	v_pk_add_f32 v[66:67], v[70:71], v[72:73] neg_lo:[0,1] neg_hi:[0,1]
	v_pk_add_f32 v[68:69], v[68:69], v[94:95] neg_lo:[0,1] neg_hi:[0,1]
	v_and_b32_sdwa v61, v66, v196 dst_sel:DWORD dst_unused:UNUSED_PAD src0_sel:WORD_1 src1_sel:DWORD
	v_and_b32_sdwa v53, v67, v196 dst_sel:DWORD dst_unused:UNUSED_PAD src0_sel:WORD_1 src1_sel:DWORD
	v_add3_u32 v61, v66, v61, s96
	v_and_b32_sdwa v66, v69, v196 dst_sel:DWORD dst_unused:UNUSED_PAD src0_sel:WORD_1 src1_sel:DWORD
	v_add3_u32 v53, v67, v53, s96
	v_and_b32_sdwa v67, v68, v196 dst_sel:DWORD dst_unused:UNUSED_PAD src0_sel:WORD_1 src1_sel:DWORD
	v_add3_u32 v66, v69, v66, s96
	v_and_b32_e32 v61, 0xffff0000, v61
	v_add3_u32 v68, v68, v67, s96
	v_and_b32_e32 v66, 0xffff0000, v66
	v_or_b32_sdwa v67, v53, v66 dst_sel:DWORD dst_unused:UNUSED_PAD src0_sel:WORD_1 src1_sel:DWORD
	v_or_b32_sdwa v66, v61, v68 dst_sel:DWORD dst_unused:UNUSED_PAD src0_sel:DWORD src1_sel:WORD_1
	v_lshl_add_u64 v[68:69], v[44:45], 0, v[74:75]
	s_mov_b64 s[56:57], 0
	global_store_dwordx2 v[68:69], v[66:67], off

.LBB0_1136:
	v_sub_f32_e32 v63, v63, v79
	v_sub_f32_e32 v62, v62, v79
	v_sub_f32_e32 v65, v65, v79
	v_sub_f32_e32 v64, v64, v79
	v_pk_mul_f32 v[62:63], v[62:63], v[80:81]
	v_mov_b32_e32 v81, v80
	v_pk_mul_f32 v[64:65], v[64:65], v[80:81]
	s_and_b64 vcc, exec, s[10:11]
	s_mov_b64 s[10:11], -1
	v_pk_fma_f32 v[2:3], v[64:65], v[166:167], v[170:171]
	v_pk_fma_f32 v[0:1], v[62:63], v[164:165], v[168:169]
	s_cbranch_vccnz .LBB0_1139
	v_and_b32_sdwa v53, v3, v196 dst_sel:DWORD dst_unused:UNUSED_PAD src0_sel:WORD_1 src1_sel:DWORD
	v_and_b32_sdwa v68, v2, v196 dst_sel:DWORD dst_unused:UNUSED_PAD src0_sel:WORD_1 src1_sel:DWORD
	v_and_b32_sdwa v69, v1, v196 dst_sel:DWORD dst_unused:UNUSED_PAD src0_sel:WORD_1 src1_sel:DWORD
	v_and_b32_sdwa v61, v0, v196 dst_sel:DWORD dst_unused:UNUSED_PAD src0_sel:WORD_1 src1_sel:DWORD
	v_add3_u32 v53, v3, v53, s96
	v_add3_u32 v71, v2, v68, s96
	v_add3_u32 v68, v1, v69, s96
	v_add3_u32 v61, v0, v61, s96
	v_and_b32_e32 v68, 0xffff0000, v68
	v_and_b32_e32 v73, 0xffff0000, v53
	v_lshl_add_u64 v[62:63], v[46:47], 0, v[74:75]
	v_mov_b32_e32 v66, v1
	v_mov_b32_e32 v67, v2
	v_and_b32_e32 v69, 0xffff0000, v71
	v_or_b32_sdwa v70, v68, v61 dst_sel:DWORD dst_unused:UNUSED_PAD src0_sel:DWORD src1_sel:WORD_1
	v_or_b32_sdwa v71, v71, v73 dst_sel:DWORD dst_unused:UNUSED_PAD src0_sel:WORD_1 src1_sel:DWORD
	v_mov_b32_e32 v64, v0
	v_mov_b32_e32 v65, v3
	v_and_b32_e32 v72, 0xffff0000, v61
	global_store_dwordx2 v[62:63], v[70:71], off
	v_pk_add_f32 v[62:63], v[66:67], v[68:69] neg_lo:[0,1] neg_hi:[0,1]
	v_pk_add_f32 v[64:65], v[64:65], v[72:73] neg_lo:[0,1] neg_hi:[0,1]
	v_and_b32_sdwa v61, v62, v196 dst_sel:DWORD dst_unused:UNUSED_PAD src0_sel:WORD_1 src1_sel:DWORD
	v_and_b32_sdwa v53, v63, v196 dst_sel:DWORD dst_unused:UNUSED_PAD src0_sel:WORD_1 src1_sel:DWORD
	v_add3_u32 v61, v62, v61, s96
	v_and_b32_sdwa v62, v65, v196 dst_sel:DWORD dst_unused:UNUSED_PAD src0_sel:WORD_1 src1_sel:DWORD
	v_add3_u32 v53, v63, v53, s96
	v_and_b32_sdwa v63, v64, v196 dst_sel:DWORD dst_unused:UNUSED_PAD src0_sel:WORD_1 src1_sel:DWORD
	v_add3_u32 v62, v65, v62, s96
	v_and_b32_e32 v61, 0xffff0000, v61
	v_add3_u32 v64, v64, v63, s96
	v_and_b32_e32 v62, 0xffff0000, v62
	v_or_b32_sdwa v63, v53, v62 dst_sel:DWORD dst_unused:UNUSED_PAD src0_sel:WORD_1 src1_sel:DWORD
	v_or_b32_sdwa v62, v61, v64 dst_sel:DWORD dst_unused:UNUSED_PAD src0_sel:DWORD src1_sel:WORD_1
	v_lshl_add_u64 v[64:65], v[48:49], 0, v[74:75]
	global_store_dwordx2 v[64:65], v[62:63], off
	s_cbranch_execz .LBB0_1140

.LBB0_1143:
	s_waitcnt vmcnt(0)
	v_mov_b32_e32 v0, 0
	s_mov_b64 s[8:9], 0
	v_mov_b64_e32 v[62:63], v[58:59]
	v_mov_b64_e32 v[64:65], v[56:57]
	v_mov_b32_e32 v53, v91
	v_mov_b32_e32 v1, v0
	v_mov_b32_e32 v80, v0
	v_mov_b32_e32 v81, v0
	v_mov_b32_e32 v74, v0
	v_mov_b32_e32 v75, v0
	v_mov_b32_e32 v72, v0
	v_mov_b32_e32 v73, v0
	v_mov_b32_e32 v70, v0
	v_mov_b32_e32 v71, v0
	v_mov_b32_e32 v68, v0
	v_mov_b32_e32 v69, v0
	v_mov_b32_e32 v66, v0
	v_mov_b32_e32 v67, v0
	v_mov_b32_e32 v2, v0
	v_mov_b32_e32 v3, v0
